# k9 + MLA unit epilogue: dwordx4 stores via v_permlane32_swap
# speedup vs baseline: 1.0031x; 1.0031x over previous
; __device__ __forceinline__ unsigned cvtpk(float lo, float hi) { f32x2_t v = {lo, hi}; bf16x2_t b = __builtin_convertvector(v, bf16x2_t); return __builtin_bit_cast(unsigned, b); }
; template <int DQK, int DV, int MODE, int QPRE, bool DIFF> ...
;     ...
;     float inv = 1.0f;
;     if (MODE != 1) { float a, b; swap32(l_run, a, b); inv = 1.0f / (a + b); }
;     ...
; #pragma unroll
;         for (int db = 0; db < NDB; ++db)
; #pragma unroll
;             for (int g = 0; g < 4; ++g) {
;                 u32x2 w; w.x = cvtpk(o[db][4 * g] * inv, o[db][4 * g + 1] * inv); w.y = cvtpk(o[db][4 * g + 2] * inv, o[db][4 * g + 3] * inv);
;                 *(u32x2*)(orow + db * 32 + 8 * g) = w;
;             }
.LBB0_1636:
	s_lshl_b32 s2, s52, 11
	s_add_u32 s2, s33, s2
	s_addc_u32 s5, s34, 0
	s_lshl_b32 s4, s53, 1
	v_mov_b32_e32 v34, v196
	s_add_u32 s4, s2, s4
	s_nop 0
	v_permlane32_swap_b32_e32 v196, v34
	s_addc_u32 s5, s5, 0
	v_lshlrev_b64 v[32:33], 11, v[168:169]
	v_add_f32_e32 v36, v196, v34
	v_lshl_add_u64 v[32:33], s[4:5], 0, v[32:33]
	v_div_scale_f32 v37, s[4:5], v36, v36, 1.0
	v_rcp_f32_e32 v38, v37
	v_lshlrev_b32_e32 v34, 3, v182
	v_ashrrev_i32_e32 v35, 31, v34
	v_lshl_add_u64 v[32:33], v[34:35], 1, v[32:33]
	v_fma_f32 v34, -v37, v38, 1.0
	v_fmac_f32_e32 v38, v34, v38
	v_div_scale_f32 v34, vcc, 1.0, v36, 1.0
	v_mul_f32_e32 v35, v34, v38
	v_fma_f32 v39, -v37, v35, v34
	v_fmac_f32_e32 v35, v39, v38
	v_fma_f32 v34, -v37, v35, v34
	v_div_fmas_f32 v34, v34, v38, v35
	v_div_fixup_f32 v34, v34, v36, 1.0
	v_pk_mul_f32 v[16:17], v[16:17], v[34:35] op_sel_hi:[1,0]
	v_pk_mul_f32 v[18:19], v[18:19], v[34:35] op_sel_hi:[1,0]
	v_pk_mul_f32 v[20:21], v[20:21], v[34:35] op_sel_hi:[1,0]
	v_pk_mul_f32 v[22:23], v[22:23], v[34:35] op_sel_hi:[1,0]
	v_pk_mul_f32 v[24:25], v[24:25], v[34:35] op_sel_hi:[1,0]
	v_pk_mul_f32 v[26:27], v[26:27], v[34:35] op_sel_hi:[1,0]
	v_pk_mul_f32 v[28:29], v[28:29], v[34:35] op_sel_hi:[1,0]
	v_pk_mul_f32 v[30:31], v[30:31], v[34:35] op_sel_hi:[1,0]
	v_pk_mul_f32 v[0:1], v[0:1], v[34:35] op_sel_hi:[1,0]
	v_pk_mul_f32 v[2:3], v[2:3], v[34:35] op_sel_hi:[1,0]
	v_pk_mul_f32 v[4:5], v[4:5], v[34:35] op_sel_hi:[1,0]
	v_pk_mul_f32 v[6:7], v[6:7], v[34:35] op_sel_hi:[1,0]
	v_pk_mul_f32 v[8:9], v[8:9], v[34:35] op_sel_hi:[1,0]
	v_pk_mul_f32 v[10:11], v[10:11], v[34:35] op_sel_hi:[1,0]
	v_pk_mul_f32 v[12:13], v[12:13], v[34:35] op_sel_hi:[1,0]
	v_pk_mul_f32 v[14:15], v[14:15], v[34:35] op_sel_hi:[1,0]
	s_add_i32 s4, s43, 1
	s_bitcmp0_b32 s43, 0
	s_mul_i32 s2, s4, s80
	s_cselect_b32 s5, s31, s88
	s_add_i32 s2, s5, s2
	v_cvt_pk_bf16_f32 v16, v16, v17
	v_cvt_pk_bf16_f32 v17, v18, v19
	v_cvt_pk_bf16_f32 v18, v20, v21
	v_cvt_pk_bf16_f32 v19, v22, v23
	v_cvt_pk_bf16_f32 v20, v24, v25
	v_cvt_pk_bf16_f32 v21, v26, v27
	v_cvt_pk_bf16_f32 v22, v28, v29
	v_cvt_pk_bf16_f32 v23, v30, v31
	v_cvt_pk_bf16_f32 v0, v0, v1
	v_cvt_pk_bf16_f32 v1, v2, v3
	v_cvt_pk_bf16_f32 v2, v4, v5
	v_cvt_pk_bf16_f32 v3, v6, v7
	v_cvt_pk_bf16_f32 v4, v8, v9
	v_cvt_pk_bf16_f32 v5, v10, v11
	v_cvt_pk_bf16_f32 v6, v12, v13
	v_cvt_pk_bf16_f32 v7, v14, v15
	s_nop 1
	v_permlane32_swap_b32_e32 v16, v18
	v_permlane32_swap_b32_e32 v17, v19
	v_permlane32_swap_b32_e32 v20, v22
	v_permlane32_swap_b32_e32 v21, v23
	v_permlane32_swap_b32_e32 v0, v2
	v_permlane32_swap_b32_e32 v1, v3
	v_permlane32_swap_b32_e32 v4, v6
	v_permlane32_swap_b32_e32 v5, v7
	s_cmpk_lt_i32 s2, 0x800
	s_mov_b32 s43, s4
	global_store_dwordx4 v[32:33], v[16:19], off
	global_store_dwordx4 v[32:33], v[20:23], off offset:32
	global_store_dwordx4 v[32:33], v[0:3], off offset:64
	global_store_dwordx4 v[32:33], v[4:7], off offset:96
	s_cbranch_scc0 .LBB0_1727
